# grid barrier: all workgroups poll the top-level generation word directly (hierarchical arrive, flat release), per-XCD generation add removed; plus write-through dwordx4 stores
# baseline (speedup 1.0000x reference)
; __device__ __forceinline__ unsigned xb_ld(unsigned* p)              { return __hip_atomic_load(p, __ATOMIC_RELAXED, __HIP_MEMORY_SCOPE_AGENT); }
; __device__ __forceinline__ unsigned xb_add(unsigned* p, unsigned v) { return __hip_atomic_fetch_add(p, v, __ATOMIC_RELAXED, __HIP_MEMORY_SCOPE_AGENT); }
; #define XB_SPIN(cond, bar) do { unsigned _sp = 0; while (cond) { __builtin_amdgcn_s_sleep(1); \
;     if ((++_sp & 255u) == 0u) { if (xb_ld(&(bar)[XB_TMO])) break; if (_sp > XB_SPIN_CAP) { atomicAdd(&(bar)[XB_TMO], 1u); break; } } } } while (0)
; __device__ __forceinline__ void xcd_barrier(const XcdBarrier& b) {
;     ...
;         const unsigned old = xb_add(&bar[XB_XSUB(b.x)], 1u);
;         const unsigned gen = old / nloc;
;         if (old + 1u == (gen + 1u) * nloc) {
;             __builtin_amdgcn_fence(__ATOMIC_RELEASE, "agent");
;             asm volatile("s_waitcnt vmcnt(0)" ::: "memory");
;             const unsigned og = xb_add(&bar[XB_TOP], 1u);
;             const unsigned tg = og / nx;
;             if (og + 1u == (tg + 1u) * nx) xb_add(&bar[XB_TOPGEN], 1u);
;             else XB_SPIN(xb_ld(&bar[XB_TOPGEN]) == tg, bar);
;             __builtin_amdgcn_fence(__ATOMIC_ACQUIRE, "agent");
;             xb_add(&bar[XB_XGEN(b.x)], 1u);
;             asm volatile("s_waitcnt vmcnt(0)" ::: "memory");
;         } else {
;             XB_SPIN(xb_ld(&bar[XB_XGEN(b.x)]) == gen, bar);
.LBB0_575:
	s_or_b64 exec, exec, s[8:9]
	v_cvt_f32_u32_e32 v4, v2
	s_waitcnt vmcnt(0)
	v_readfirstlane_b32 s2, v3
	v_sub_u32_e32 v3, 0, v2
	v_rcp_iflag_f32_e32 v4, v4
	v_add_u32_e32 v5, s2, v1
	v_mul_f32_e32 v4, 0x4f7ffffe, v4
	v_cvt_u32_f32_e32 v4, v4
	v_mul_lo_u32 v1, v3, v4
	v_mul_hi_u32 v1, v4, v1
	v_add_u32_e32 v1, v4, v1
	v_mul_hi_u32 v1, v5, v1
	v_mul_lo_u32 v3, v1, v2
	v_sub_u32_e32 v3, v5, v3
	v_add_u32_e32 v4, 1, v1
	v_cmp_ge_u32_e32 vcc, v3, v2
	s_nop 1
	v_cndmask_b32_e32 v1, v1, v4, vcc
	v_sub_u32_e32 v4, v3, v2
	v_cndmask_b32_e32 v3, v3, v4, vcc
	v_add_u32_e32 v4, 1, v1
	v_cmp_ge_u32_e32 vcc, v3, v2
	v_add_u32_e32 v3, 1, v5
	s_nop 0
	v_cndmask_b32_e32 v1, v1, v4, vcc
	v_mul_lo_u32 v4, v2, v1
	v_add_u32_e32 v2, v4, v2
	v_cmp_ne_u32_e32 vcc, v3, v2
	s_and_saveexec_b64 s[6:7], vcc
	s_xor_b64 s[6:7], exec, s[6:7]
	s_cbranch_execz .LBB0_589
	s_waitcnt lgkmcnt(0)
	s_add_u32 s12, s74, 0x43303500
	s_addc_u32 s13, s75, 0
	v_mov_b32_e32 v0, 0
	global_load_dword v0, v0, s[12:13] sc1
	s_waitcnt vmcnt(0)
	v_cmp_eq_u32_e32 vcc, v0, v1
	s_and_saveexec_b64 s[8:9], vcc
	s_cbranch_execz .LBB0_588
	s_add_u32 s10, s74, 0x43300200
	s_addc_u32 s11, s75, 0
	s_mov_b32 s2, 1
	s_mov_b64 s[14:15], 0
	v_mov_b32_e32 v0, 0
	s_branch .LBB0_579

; __device__ __forceinline__ unsigned xb_add(unsigned* p, unsigned v) { return __hip_atomic_fetch_add(p, v, __ATOMIC_RELAXED, __HIP_MEMORY_SCOPE_AGENT); }
; __device__ __forceinline__ void xcd_barrier(const XcdBarrier& b) {
;     ...
;             __builtin_amdgcn_fence(__ATOMIC_ACQUIRE, "agent");
;             xb_add(&bar[XB_XGEN(b.x)], 1u);
;             asm volatile("s_waitcnt vmcnt(0)" ::: "memory");
.LBB0_606:
	s_or_b64 exec, exec, s[6:7]
	s_mov_b64 s[6:7], exec
	v_mbcnt_lo_u32_b32 v0, s6, 0
	v_mbcnt_hi_u32_b32 v0, s7, v0
	v_cmp_eq_u32_e32 vcc, 0, v0
	s_waitcnt vmcnt(0)
	buffer_inv sc1
	s_and_saveexec_b64 s[8:9], vcc
	s_cbranch_execz .LBB0_608
	s_bcnt1_i32_b64 s2, s[6:7]
	v_mov_b32_e32 v0, 0x2000
	v_mov_b32_e32 v1, s2
.LBB0_608:
	s_or_b64 exec, exec, s[8:9]
	s_waitcnt vmcnt(0)

; __device__ __forceinline__ unsigned xb_add(unsigned* p, unsigned v) { return __hip_atomic_fetch_add(p, v, __ATOMIC_RELAXED, __HIP_MEMORY_SCOPE_AGENT); }
; __device__ __forceinline__ void xcd_barrier(const XcdBarrier& b) {
;     ...
;             __builtin_amdgcn_fence(__ATOMIC_ACQUIRE, "agent");
;             xb_add(&bar[XB_XGEN(b.x)], 1u);
;             asm volatile("s_waitcnt vmcnt(0)" ::: "memory");
.LBB0_804:
	s_or_b64 exec, exec, s[6:7]
	s_mov_b64 s[6:7], exec
	v_mbcnt_lo_u32_b32 v0, s6, 0
	v_mbcnt_hi_u32_b32 v0, s7, v0
	v_cmp_eq_u32_e32 vcc, 0, v0
	s_waitcnt vmcnt(0)
	buffer_inv sc1
	s_and_saveexec_b64 s[8:9], vcc
	s_cbranch_execz .LBB0_806
	s_bcnt1_i32_b64 s2, s[6:7]
	v_mov_b32_e32 v0, 0x2000
	v_mov_b32_e32 v1, s2
.LBB0_806:
	s_or_b64 exec, exec, s[8:9]
	s_waitcnt vmcnt(0)

; __device__ __forceinline__ unsigned xb_ld(unsigned* p)              { return __hip_atomic_load(p, __ATOMIC_RELAXED, __HIP_MEMORY_SCOPE_AGENT); }
; __device__ __forceinline__ unsigned xb_add(unsigned* p, unsigned v) { return __hip_atomic_fetch_add(p, v, __ATOMIC_RELAXED, __HIP_MEMORY_SCOPE_AGENT); }
; #define XB_SPIN(cond, bar) do { unsigned _sp = 0; while (cond) { __builtin_amdgcn_s_sleep(1); \
;     if ((++_sp & 255u) == 0u) { if (xb_ld(&(bar)[XB_TMO])) break; if (_sp > XB_SPIN_CAP) { atomicAdd(&(bar)[XB_TMO], 1u); break; } } } } while (0)
; __device__ __forceinline__ void xcd_barrier(const XcdBarrier& b) {
;     ...
;         const unsigned old = xb_add(&bar[XB_XSUB(b.x)], 1u);
;         const unsigned gen = old / nloc;
;         if (old + 1u == (gen + 1u) * nloc) {
;             __builtin_amdgcn_fence(__ATOMIC_RELEASE, "agent");
;             asm volatile("s_waitcnt vmcnt(0)" ::: "memory");
;             const unsigned og = xb_add(&bar[XB_TOP], 1u);
;             const unsigned tg = og / nx;
;             if (og + 1u == (tg + 1u) * nx) xb_add(&bar[XB_TOPGEN], 1u);
;             else XB_SPIN(xb_ld(&bar[XB_TOPGEN]) == tg, bar);
;             __builtin_amdgcn_fence(__ATOMIC_ACQUIRE, "agent");
;             xb_add(&bar[XB_XGEN(b.x)], 1u);
;             asm volatile("s_waitcnt vmcnt(0)" ::: "memory");
;         } else {
;             XB_SPIN(xb_ld(&bar[XB_XGEN(b.x)]) == gen, bar);
.LBB0_942:
	s_or_b64 exec, exec, s[10:11]
	v_cvt_f32_u32_e32 v4, v2
	s_waitcnt vmcnt(0)
	v_readfirstlane_b32 s2, v3
	v_sub_u32_e32 v3, 0, v2
	v_rcp_iflag_f32_e32 v4, v4
	v_add_u32_e32 v5, s2, v1
	v_mul_f32_e32 v4, 0x4f7ffffe, v4
	v_cvt_u32_f32_e32 v4, v4
	v_mul_lo_u32 v1, v3, v4
	v_mul_hi_u32 v1, v4, v1
	v_add_u32_e32 v1, v4, v1
	v_mul_hi_u32 v1, v5, v1
	v_mul_lo_u32 v3, v1, v2
	v_sub_u32_e32 v3, v5, v3
	v_add_u32_e32 v4, 1, v1
	v_cmp_ge_u32_e32 vcc, v3, v2
	s_nop 1
	v_cndmask_b32_e32 v1, v1, v4, vcc
	v_sub_u32_e32 v4, v3, v2
	v_cndmask_b32_e32 v3, v3, v4, vcc
	v_add_u32_e32 v4, 1, v1
	v_cmp_ge_u32_e32 vcc, v3, v2
	v_add_u32_e32 v3, 1, v5
	s_nop 0
	v_cndmask_b32_e32 v1, v1, v4, vcc
	v_mul_lo_u32 v4, v2, v1
	v_add_u32_e32 v2, v4, v2
	v_cmp_ne_u32_e32 vcc, v3, v2
	s_and_saveexec_b64 s[6:7], vcc
	s_xor_b64 s[8:9], exec, s[6:7]
	s_cbranch_execz .LBB0_956
	s_waitcnt lgkmcnt(0)
	s_add_u32 s14, s74, 0x43303500
	s_addc_u32 s15, s75, 0
	v_mov_b32_e32 v0, 0
	global_load_dword v0, v0, s[14:15] sc1
	s_waitcnt vmcnt(0)
	v_cmp_eq_u32_e32 vcc, v0, v1
	s_and_saveexec_b64 s[10:11], vcc
	s_cbranch_execz .LBB0_955
	s_add_u32 s12, s74, 0x43300200
	s_addc_u32 s13, s75, 0
	s_mov_b32 s2, 1
	s_mov_b64 s[16:17], 0
	v_mov_b32_e32 v0, 0
	s_branch .LBB0_946

; __device__ __forceinline__ unsigned xb_add(unsigned* p, unsigned v) { return __hip_atomic_fetch_add(p, v, __ATOMIC_RELAXED, __HIP_MEMORY_SCOPE_AGENT); }
; __device__ __forceinline__ void xcd_barrier(const XcdBarrier& b) {
;     ...
;             __builtin_amdgcn_fence(__ATOMIC_ACQUIRE, "agent");
;             xb_add(&bar[XB_XGEN(b.x)], 1u);
;             asm volatile("s_waitcnt vmcnt(0)" ::: "memory");
.LBB0_973:
	s_or_b64 exec, exec, s[8:9]
	s_mov_b64 s[8:9], exec
	v_mbcnt_lo_u32_b32 v0, s8, 0
	v_mbcnt_hi_u32_b32 v0, s9, v0
	v_cmp_eq_u32_e32 vcc, 0, v0
	s_waitcnt vmcnt(0)
	buffer_inv sc1
	s_and_saveexec_b64 s[10:11], vcc
	s_cbranch_execz .LBB0_975
	s_bcnt1_i32_b64 s2, s[8:9]
	v_mov_b32_e32 v0, 0x2000
	v_mov_b32_e32 v1, s2
.LBB0_975:
	s_or_b64 exec, exec, s[10:11]
	s_waitcnt vmcnt(0)

; __device__ __forceinline__ unsigned xb_add(unsigned* p, unsigned v) { return __hip_atomic_fetch_add(p, v, __ATOMIC_RELAXED, __HIP_MEMORY_SCOPE_AGENT); }
; __device__ __forceinline__ void xcd_barrier(const XcdBarrier& b) {
;     ...
;             __builtin_amdgcn_fence(__ATOMIC_ACQUIRE, "agent");
;             xb_add(&bar[XB_XGEN(b.x)], 1u);
;             asm volatile("s_waitcnt vmcnt(0)" ::: "memory");
.LBB0_1044:
	s_or_b64 exec, exec, s[8:9]
	s_mov_b64 s[8:9], exec
	v_mbcnt_lo_u32_b32 v0, s8, 0
	v_mbcnt_hi_u32_b32 v0, s9, v0
	v_cmp_eq_u32_e32 vcc, 0, v0
	s_waitcnt vmcnt(0)
	buffer_inv sc1
	s_and_saveexec_b64 s[10:11], vcc
	s_cbranch_execz .LBB0_1046
	s_bcnt1_i32_b64 s2, s[8:9]
	v_mov_b32_e32 v0, 0x2000
	v_mov_b32_e32 v1, s2
.LBB0_1046:
	s_or_b64 exec, exec, s[10:11]
	s_waitcnt vmcnt(0)

; __device__ __forceinline__ unsigned xb_add(unsigned* p, unsigned v) { return __hip_atomic_fetch_add(p, v, __ATOMIC_RELAXED, __HIP_MEMORY_SCOPE_AGENT); }
; __device__ __forceinline__ void xcd_barrier(const XcdBarrier& b) {
;     ...
;             __builtin_amdgcn_fence(__ATOMIC_ACQUIRE, "agent");
;             xb_add(&bar[XB_XGEN(b.x)], 1u);
;             asm volatile("s_waitcnt vmcnt(0)" ::: "memory");
.LBB0_1138:
	s_or_b64 exec, exec, s[8:9]
	s_mov_b64 s[8:9], exec
	v_mbcnt_lo_u32_b32 v0, s8, 0
	v_mbcnt_hi_u32_b32 v0, s9, v0
	v_cmp_eq_u32_e32 vcc, 0, v0
	s_waitcnt vmcnt(0)
	buffer_inv sc1
	s_and_saveexec_b64 s[10:11], vcc
	s_cbranch_execz .LBB0_1140
	s_bcnt1_i32_b64 s2, s[8:9]
	v_mov_b32_e32 v0, 0x2000
	v_mov_b32_e32 v1, s2
.LBB0_1140:
	s_or_b64 exec, exec, s[10:11]
	s_waitcnt vmcnt(0)

; __device__ __forceinline__ unsigned xb_ld(unsigned* p)              { return __hip_atomic_load(p, __ATOMIC_RELAXED, __HIP_MEMORY_SCOPE_AGENT); }
; __device__ __forceinline__ unsigned xb_add(unsigned* p, unsigned v) { return __hip_atomic_fetch_add(p, v, __ATOMIC_RELAXED, __HIP_MEMORY_SCOPE_AGENT); }
; #define XB_SPIN(cond, bar) do { unsigned _sp = 0; while (cond) { __builtin_amdgcn_s_sleep(1); \
;     if ((++_sp & 255u) == 0u) { if (xb_ld(&(bar)[XB_TMO])) break; if (_sp > XB_SPIN_CAP) { atomicAdd(&(bar)[XB_TMO], 1u); break; } } } } while (0)
; __device__ __forceinline__ void xcd_barrier(const XcdBarrier& b) {
;     ...
;         const unsigned old = xb_add(&bar[XB_XSUB(b.x)], 1u);
;         const unsigned gen = old / nloc;
;         if (old + 1u == (gen + 1u) * nloc) {
;             __builtin_amdgcn_fence(__ATOMIC_RELEASE, "agent");
;             asm volatile("s_waitcnt vmcnt(0)" ::: "memory");
;             const unsigned og = xb_add(&bar[XB_TOP], 1u);
;             const unsigned tg = og / nx;
;             if (og + 1u == (tg + 1u) * nx) xb_add(&bar[XB_TOPGEN], 1u);
;             else XB_SPIN(xb_ld(&bar[XB_TOPGEN]) == tg, bar);
;             __builtin_amdgcn_fence(__ATOMIC_ACQUIRE, "agent");
;             xb_add(&bar[XB_XGEN(b.x)], 1u);
;             asm volatile("s_waitcnt vmcnt(0)" ::: "memory");
;         } else {
;             XB_SPIN(xb_ld(&bar[XB_XGEN(b.x)]) == gen, bar);
.LBB0_1241:
	s_or_b64 exec, exec, s[12:13]
	v_cvt_f32_u32_e32 v4, v2
	s_waitcnt vmcnt(0)
	v_readfirstlane_b32 s2, v3
	v_sub_u32_e32 v3, 0, v2
	v_rcp_iflag_f32_e32 v4, v4
	v_add_u32_e32 v5, s2, v1
	v_mul_f32_e32 v4, 0x4f7ffffe, v4
	v_cvt_u32_f32_e32 v4, v4
	v_mul_lo_u32 v1, v3, v4
	v_mul_hi_u32 v1, v4, v1
	v_add_u32_e32 v1, v4, v1
	v_mul_hi_u32 v1, v5, v1
	v_mul_lo_u32 v3, v1, v2
	v_sub_u32_e32 v3, v5, v3
	v_add_u32_e32 v4, 1, v1
	v_cmp_ge_u32_e32 vcc, v3, v2
	s_nop 1
	v_cndmask_b32_e32 v1, v1, v4, vcc
	v_sub_u32_e32 v4, v3, v2
	v_cndmask_b32_e32 v3, v3, v4, vcc
	v_add_u32_e32 v4, 1, v1
	v_cmp_ge_u32_e32 vcc, v3, v2
	v_add_u32_e32 v3, 1, v5
	s_nop 0
	v_cndmask_b32_e32 v1, v1, v4, vcc
	v_mul_lo_u32 v4, v2, v1
	v_add_u32_e32 v2, v4, v2
	v_cmp_ne_u32_e32 vcc, v3, v2
	s_and_saveexec_b64 s[6:7], vcc
	s_xor_b64 s[10:11], exec, s[6:7]
	s_cbranch_execz .LBB0_1255
	s_waitcnt lgkmcnt(0)
	s_add_u32 s16, s74, 0x43303500
	s_addc_u32 s17, s75, 0
	v_mov_b32_e32 v0, 0
	global_load_dword v0, v0, s[16:17] sc1
	s_waitcnt vmcnt(0)
	v_cmp_eq_u32_e32 vcc, v0, v1
	s_and_saveexec_b64 s[12:13], vcc
	s_cbranch_execz .LBB0_1254
	s_add_u32 s14, s74, 0x43300200
	s_addc_u32 s15, s75, 0
	s_mov_b32 s2, 1
	s_mov_b64 s[18:19], 0
	v_mov_b32_e32 v0, 0
	s_branch .LBB0_1245

; __device__ __forceinline__ unsigned xb_add(unsigned* p, unsigned v) { return __hip_atomic_fetch_add(p, v, __ATOMIC_RELAXED, __HIP_MEMORY_SCOPE_AGENT); }
; __device__ __forceinline__ void xcd_barrier(const XcdBarrier& b) {
;     ...
;             __builtin_amdgcn_fence(__ATOMIC_ACQUIRE, "agent");
;             xb_add(&bar[XB_XGEN(b.x)], 1u);
;             asm volatile("s_waitcnt vmcnt(0)" ::: "memory");
.LBB0_1272:
	s_or_b64 exec, exec, s[10:11]
	s_mov_b64 s[10:11], exec
	v_mbcnt_lo_u32_b32 v0, s10, 0
	v_mbcnt_hi_u32_b32 v0, s11, v0
	v_cmp_eq_u32_e32 vcc, 0, v0
	s_waitcnt vmcnt(0)
	buffer_inv sc1
	s_and_saveexec_b64 s[12:13], vcc
	s_cbranch_execz .LBB0_1274
	s_bcnt1_i32_b64 s2, s[10:11]
	v_mov_b32_e32 v0, 0x2000
	v_mov_b32_e32 v1, s2
.LBB0_1274:
	s_or_b64 exec, exec, s[12:13]
	s_waitcnt vmcnt(0)

; __device__ __forceinline__ unsigned xb_add(unsigned* p, unsigned v) { return __hip_atomic_fetch_add(p, v, __ATOMIC_RELAXED, __HIP_MEMORY_SCOPE_AGENT); }
; __device__ __forceinline__ void xcd_barrier(const XcdBarrier& b) {
;     ...
;             __builtin_amdgcn_fence(__ATOMIC_ACQUIRE, "agent");
;             xb_add(&bar[XB_XGEN(b.x)], 1u);
;             asm volatile("s_waitcnt vmcnt(0)" ::: "memory");
.LBB0_1370:
	s_or_b64 exec, exec, s[10:11]
	s_mov_b64 s[10:11], exec
	v_mbcnt_lo_u32_b32 v0, s10, 0
	v_mbcnt_hi_u32_b32 v0, s11, v0
	v_cmp_eq_u32_e32 vcc, 0, v0
	s_waitcnt vmcnt(0)
	buffer_inv sc1
	s_and_saveexec_b64 s[12:13], vcc
	s_cbranch_execz .LBB0_1372
	s_bcnt1_i32_b64 s2, s[10:11]
	v_mov_b32_e32 v0, 0x2000
	v_mov_b32_e32 v1, s2
.LBB0_1372:
	s_or_b64 exec, exec, s[12:13]
	s_waitcnt vmcnt(0)

; __device__ __forceinline__ unsigned xb_add(unsigned* p, unsigned v) { return __hip_atomic_fetch_add(p, v, __ATOMIC_RELAXED, __HIP_MEMORY_SCOPE_AGENT); }
; __device__ __forceinline__ void xcd_barrier(const XcdBarrier& b) {
;     ...
;             __builtin_amdgcn_fence(__ATOMIC_ACQUIRE, "agent");
;             xb_add(&bar[XB_XGEN(b.x)], 1u);
;             asm volatile("s_waitcnt vmcnt(0)" ::: "memory");
.LBB0_1595:
	s_or_b64 exec, exec, s[10:11]
	s_mov_b64 s[10:11], exec
	v_mbcnt_lo_u32_b32 v0, s10, 0
	v_mbcnt_hi_u32_b32 v0, s11, v0
	v_cmp_eq_u32_e32 vcc, 0, v0
	s_waitcnt vmcnt(0)
	buffer_inv sc1
	s_and_saveexec_b64 s[12:13], vcc
	s_cbranch_execz .LBB0_1597
	s_bcnt1_i32_b64 s2, s[10:11]
	v_mov_b32_e32 v0, 0x2000
	v_mov_b32_e32 v1, s2
.LBB0_1597:
	s_or_b64 exec, exec, s[12:13]
	s_waitcnt vmcnt(0)

; __device__ __forceinline__ unsigned xb_ld(unsigned* p)              { return __hip_atomic_load(p, __ATOMIC_RELAXED, __HIP_MEMORY_SCOPE_AGENT); }
; __device__ __forceinline__ unsigned xb_add(unsigned* p, unsigned v) { return __hip_atomic_fetch_add(p, v, __ATOMIC_RELAXED, __HIP_MEMORY_SCOPE_AGENT); }
; #define XB_SPIN(cond, bar) do { unsigned _sp = 0; while (cond) { __builtin_amdgcn_s_sleep(1); \
;     if ((++_sp & 255u) == 0u) { if (xb_ld(&(bar)[XB_TMO])) break; if (_sp > XB_SPIN_CAP) { atomicAdd(&(bar)[XB_TMO], 1u); break; } } } } while (0)
; __device__ __forceinline__ void xcd_barrier(const XcdBarrier& b) {
;     ...
;         const unsigned old = xb_add(&bar[XB_XSUB(b.x)], 1u);
;         const unsigned gen = old / nloc;
;         if (old + 1u == (gen + 1u) * nloc) {
;             __builtin_amdgcn_fence(__ATOMIC_RELEASE, "agent");
;             asm volatile("s_waitcnt vmcnt(0)" ::: "memory");
;             const unsigned og = xb_add(&bar[XB_TOP], 1u);
;             const unsigned tg = og / nx;
;             if (og + 1u == (tg + 1u) * nx) xb_add(&bar[XB_TOPGEN], 1u);
;             else XB_SPIN(xb_ld(&bar[XB_TOPGEN]) == tg, bar);
;             __builtin_amdgcn_fence(__ATOMIC_ACQUIRE, "agent");
;             xb_add(&bar[XB_XGEN(b.x)], 1u);
;             asm volatile("s_waitcnt vmcnt(0)" ::: "memory");
;         } else {
;             XB_SPIN(xb_ld(&bar[XB_XGEN(b.x)]) == gen, bar);
.LBB0_1644:
	s_or_b64 exec, exec, s[14:15]
	v_cvt_f32_u32_e32 v4, v2
	s_waitcnt vmcnt(0)
	v_readfirstlane_b32 s2, v3
	v_sub_u32_e32 v3, 0, v2
	v_rcp_iflag_f32_e32 v4, v4
	v_add_u32_e32 v5, s2, v1
	v_mul_f32_e32 v4, 0x4f7ffffe, v4
	v_cvt_u32_f32_e32 v4, v4
	v_mul_lo_u32 v1, v3, v4
	v_mul_hi_u32 v1, v4, v1
	v_add_u32_e32 v1, v4, v1
	v_mul_hi_u32 v1, v5, v1
	v_mul_lo_u32 v3, v1, v2
	v_sub_u32_e32 v3, v5, v3
	v_add_u32_e32 v4, 1, v1
	v_cmp_ge_u32_e32 vcc, v3, v2
	s_nop 1
	v_cndmask_b32_e32 v1, v1, v4, vcc
	v_sub_u32_e32 v4, v3, v2
	v_cndmask_b32_e32 v3, v3, v4, vcc
	v_add_u32_e32 v4, 1, v1
	v_cmp_ge_u32_e32 vcc, v3, v2
	v_add_u32_e32 v3, 1, v5
	s_nop 0
	v_cndmask_b32_e32 v1, v1, v4, vcc
	v_mul_lo_u32 v4, v2, v1
	v_add_u32_e32 v2, v4, v2
	v_cmp_ne_u32_e32 vcc, v3, v2
	s_and_saveexec_b64 s[6:7], vcc
	s_xor_b64 s[12:13], exec, s[6:7]
	s_cbranch_execz .LBB0_1658
	s_waitcnt lgkmcnt(0)
	s_add_u32 s18, s74, 0x43303500
	s_addc_u32 s19, s75, 0
	v_mov_b32_e32 v0, 0
	global_load_dword v0, v0, s[18:19] sc1
	s_waitcnt vmcnt(0)
	v_cmp_eq_u32_e32 vcc, v0, v1
	s_and_saveexec_b64 s[14:15], vcc
	s_cbranch_execz .LBB0_1657
	s_add_u32 s16, s74, 0x43300200
	s_addc_u32 s17, s75, 0
	s_mov_b32 s2, 1
	s_mov_b64 s[20:21], 0
	v_mov_b32_e32 v0, 0
	s_branch .LBB0_1648

; __device__ __forceinline__ unsigned xb_add(unsigned* p, unsigned v) { return __hip_atomic_fetch_add(p, v, __ATOMIC_RELAXED, __HIP_MEMORY_SCOPE_AGENT); }
; __device__ __forceinline__ void xcd_barrier(const XcdBarrier& b) {
;     ...
;             __builtin_amdgcn_fence(__ATOMIC_ACQUIRE, "agent");
;             xb_add(&bar[XB_XGEN(b.x)], 1u);
;             asm volatile("s_waitcnt vmcnt(0)" ::: "memory");
.LBB0_1675:
	s_or_b64 exec, exec, s[12:13]
	s_mov_b64 s[12:13], exec
	v_mbcnt_lo_u32_b32 v0, s12, 0
	v_mbcnt_hi_u32_b32 v0, s13, v0
	v_cmp_eq_u32_e32 vcc, 0, v0
	s_waitcnt vmcnt(0)
	buffer_inv sc1
	s_and_saveexec_b64 s[14:15], vcc
	s_cbranch_execz .LBB0_1677
	s_bcnt1_i32_b64 s2, s[12:13]
	v_mov_b32_e32 v0, 0x2000
	v_mov_b32_e32 v1, s2
.LBB0_1677:
	s_or_b64 exec, exec, s[14:15]
	s_waitcnt vmcnt(0)

; __device__ __forceinline__ unsigned xb_add(unsigned* p, unsigned v) { return __hip_atomic_fetch_add(p, v, __ATOMIC_RELAXED, __HIP_MEMORY_SCOPE_AGENT); }
; __device__ __forceinline__ void xcd_barrier(const XcdBarrier& b) {
;     ...
;             __builtin_amdgcn_fence(__ATOMIC_ACQUIRE, "agent");
;             xb_add(&bar[XB_XGEN(b.x)], 1u);
;             asm volatile("s_waitcnt vmcnt(0)" ::: "memory");
.LBB0_1777:
	s_or_b64 exec, exec, s[12:13]
	s_mov_b64 s[12:13], exec
	v_mbcnt_lo_u32_b32 v0, s12, 0
	v_mbcnt_hi_u32_b32 v0, s13, v0
	v_cmp_eq_u32_e32 vcc, 0, v0
	s_waitcnt vmcnt(0)
	buffer_inv sc1
	s_and_saveexec_b64 s[14:15], vcc
	s_cbranch_execz .LBB0_1779
	s_bcnt1_i32_b64 s2, s[12:13]
	v_mov_b32_e32 v0, 0x2000
	v_mov_b32_e32 v1, s2
.LBB0_1779:
	s_or_b64 exec, exec, s[14:15]
	s_waitcnt vmcnt(0)

; __device__ __forceinline__ unsigned xb_add(unsigned* p, unsigned v) { return __hip_atomic_fetch_add(p, v, __ATOMIC_RELAXED, __HIP_MEMORY_SCOPE_AGENT); }
; __device__ __forceinline__ void xcd_barrier(const XcdBarrier& b) {
;     ...
;             __builtin_amdgcn_fence(__ATOMIC_ACQUIRE, "agent");
;             xb_add(&bar[XB_XGEN(b.x)], 1u);
;             asm volatile("s_waitcnt vmcnt(0)" ::: "memory");
.LBB0_1911:
	s_or_b64 exec, exec, s[12:13]
	s_mov_b64 s[12:13], exec
	v_mbcnt_lo_u32_b32 v0, s12, 0
	v_mbcnt_hi_u32_b32 v0, s13, v0
	v_cmp_eq_u32_e32 vcc, 0, v0
	s_waitcnt vmcnt(0)
	buffer_inv sc1
	s_and_saveexec_b64 s[14:15], vcc
	s_cbranch_execz .LBB0_1913
	s_bcnt1_i32_b64 s2, s[12:13]
	v_mov_b32_e32 v0, 0x2000
	v_mov_b32_e32 v1, s2
.LBB0_1913:
	s_or_b64 exec, exec, s[14:15]
	s_waitcnt vmcnt(0)

; __device__ __forceinline__ unsigned xb_add(unsigned* p, unsigned v) { return __hip_atomic_fetch_add(p, v, __ATOMIC_RELAXED, __HIP_MEMORY_SCOPE_AGENT); }
; __device__ __forceinline__ void xcd_barrier(const XcdBarrier& b) {
;     ...
;             __builtin_amdgcn_fence(__ATOMIC_ACQUIRE, "agent");
;             xb_add(&bar[XB_XGEN(b.x)], 1u);
;             asm volatile("s_waitcnt vmcnt(0)" ::: "memory");
.LBB0_2009:
	s_or_b64 exec, exec, s[12:13]
	s_mov_b64 s[12:13], exec
	v_mbcnt_lo_u32_b32 v0, s12, 0
	v_mbcnt_hi_u32_b32 v0, s13, v0
	v_cmp_eq_u32_e32 vcc, 0, v0
	s_waitcnt vmcnt(0)
	buffer_inv sc1
	s_and_saveexec_b64 s[14:15], vcc
	s_cbranch_execz .LBB0_2011
	s_bcnt1_i32_b64 s2, s[12:13]
	v_mov_b32_e32 v0, 0x2000
	v_mov_b32_e32 v1, s2
.LBB0_2011:
	s_or_b64 exec, exec, s[14:15]
	s_waitcnt vmcnt(0)

; __device__ __forceinline__ unsigned xb_ld(unsigned* p)              { return __hip_atomic_load(p, __ATOMIC_RELAXED, __HIP_MEMORY_SCOPE_AGENT); }
; __device__ __forceinline__ unsigned xb_add(unsigned* p, unsigned v) { return __hip_atomic_fetch_add(p, v, __ATOMIC_RELAXED, __HIP_MEMORY_SCOPE_AGENT); }
; #define XB_SPIN(cond, bar) do { unsigned _sp = 0; while (cond) { __builtin_amdgcn_s_sleep(1); \
;     if ((++_sp & 255u) == 0u) { if (xb_ld(&(bar)[XB_TMO])) break; if (_sp > XB_SPIN_CAP) { atomicAdd(&(bar)[XB_TMO], 1u); break; } } } } while (0)
; __device__ __forceinline__ void xcd_barrier(const XcdBarrier& b) {
;     ...
;         const unsigned old = xb_add(&bar[XB_XSUB(b.x)], 1u);
;         const unsigned gen = old / nloc;
;         if (old + 1u == (gen + 1u) * nloc) {
;             __builtin_amdgcn_fence(__ATOMIC_RELEASE, "agent");
;             asm volatile("s_waitcnt vmcnt(0)" ::: "memory");
;             const unsigned og = xb_add(&bar[XB_TOP], 1u);
;             const unsigned tg = og / nx;
;             if (og + 1u == (tg + 1u) * nx) xb_add(&bar[XB_TOPGEN], 1u);
;             else XB_SPIN(xb_ld(&bar[XB_TOPGEN]) == tg, bar);
;             __builtin_amdgcn_fence(__ATOMIC_ACQUIRE, "agent");
;             xb_add(&bar[XB_XGEN(b.x)], 1u);
;             asm volatile("s_waitcnt vmcnt(0)" ::: "memory");
;         } else {
;             XB_SPIN(xb_ld(&bar[XB_XGEN(b.x)]) == gen, bar);
.LBB0_2049:
	s_or_b64 exec, exec, s[10:11]
	v_cvt_f32_u32_e32 v5, v3
	s_waitcnt vmcnt(0)
	v_readfirstlane_b32 s2, v4
	v_sub_u32_e32 v4, 0, v3
	v_rcp_iflag_f32_e32 v5, v5
	v_add_u32_e32 v6, s2, v0
	v_mul_f32_e32 v5, 0x4f7ffffe, v5
	v_cvt_u32_f32_e32 v5, v5
	v_mul_lo_u32 v0, v4, v5
	v_mul_hi_u32 v0, v5, v0
	v_add_u32_e32 v0, v5, v0
	v_mul_hi_u32 v0, v6, v0
	v_mul_lo_u32 v4, v0, v3
	v_sub_u32_e32 v4, v6, v4
	v_add_u32_e32 v5, 1, v0
	v_cmp_ge_u32_e32 vcc, v4, v3
	s_nop 1
	v_cndmask_b32_e32 v0, v0, v5, vcc
	v_sub_u32_e32 v5, v4, v3
	v_cndmask_b32_e32 v4, v4, v5, vcc
	v_add_u32_e32 v5, 1, v0
	v_cmp_ge_u32_e32 vcc, v4, v3
	v_add_u32_e32 v4, 1, v6
	s_nop 0
	v_cndmask_b32_e32 v0, v0, v5, vcc
	v_mul_lo_u32 v5, v3, v0
	v_add_u32_e32 v3, v5, v3
	v_cmp_ne_u32_e32 vcc, v4, v3
	s_and_saveexec_b64 s[2:3], vcc
	s_xor_b64 s[10:11], exec, s[2:3]
	s_cbranch_execz .LBB0_2063
	s_waitcnt lgkmcnt(0)
	global_load_dword v2, v1, s[68:69] sc1
	s_waitcnt vmcnt(0)
	v_cmp_eq_u32_e32 vcc, v2, v0
	s_and_saveexec_b64 s[12:13], vcc
	s_cbranch_execz .LBB0_2062
	s_mov_b32 s2, 1
	s_mov_b64 s[14:15], 0
	s_branch .LBB0_2053

; __device__ __forceinline__ unsigned xb_add(unsigned* p, unsigned v) { return __hip_atomic_fetch_add(p, v, __ATOMIC_RELAXED, __HIP_MEMORY_SCOPE_AGENT); }
; __device__ __forceinline__ void xcd_barrier(const XcdBarrier& b) {
;     ...
;             __builtin_amdgcn_fence(__ATOMIC_ACQUIRE, "agent");
;             xb_add(&bar[XB_XGEN(b.x)], 1u);
;             asm volatile("s_waitcnt vmcnt(0)" ::: "memory");
.LBB0_2080:
	s_or_b64 exec, exec, s[10:11]
	s_mov_b64 s[10:11], exec
	v_mbcnt_lo_u32_b32 v0, s10, 0
	v_mbcnt_hi_u32_b32 v0, s11, v0
	v_cmp_eq_u32_e32 vcc, 0, v0
	s_waitcnt vmcnt(0)
	buffer_inv sc1
	s_and_saveexec_b64 s[12:13], vcc
	s_cbranch_execz .LBB0_2082
	s_bcnt1_i32_b64 s2, s[10:11]
	v_mov_b32_e32 v0, s2
.LBB0_2082:
	s_or_b64 exec, exec, s[12:13]
	s_waitcnt vmcnt(0)

; __device__ __forceinline__ unsigned xb_ld(unsigned* p)              { return __hip_atomic_load(p, __ATOMIC_RELAXED, __HIP_MEMORY_SCOPE_AGENT); }
; __device__ __forceinline__ unsigned xb_add(unsigned* p, unsigned v) { return __hip_atomic_fetch_add(p, v, __ATOMIC_RELAXED, __HIP_MEMORY_SCOPE_AGENT); }
; #define XB_SPIN(cond, bar) do { unsigned _sp = 0; while (cond) { __builtin_amdgcn_s_sleep(1); \
;     if ((++_sp & 255u) == 0u) { if (xb_ld(&(bar)[XB_TMO])) break; if (_sp > XB_SPIN_CAP) { atomicAdd(&(bar)[XB_TMO], 1u); break; } } } } while (0)
; __device__ __forceinline__ void xcd_barrier(const XcdBarrier& b) {
;     ...
;         const unsigned old = xb_add(&bar[XB_XSUB(b.x)], 1u);
;         const unsigned gen = old / nloc;
;         if (old + 1u == (gen + 1u) * nloc) {
;             __builtin_amdgcn_fence(__ATOMIC_RELEASE, "agent");
;             asm volatile("s_waitcnt vmcnt(0)" ::: "memory");
;             const unsigned og = xb_add(&bar[XB_TOP], 1u);
;             const unsigned tg = og / nx;
;             if (og + 1u == (tg + 1u) * nx) xb_add(&bar[XB_TOPGEN], 1u);
;             else XB_SPIN(xb_ld(&bar[XB_TOPGEN]) == tg, bar);
;             __builtin_amdgcn_fence(__ATOMIC_ACQUIRE, "agent");
;             xb_add(&bar[XB_XGEN(b.x)], 1u);
;             asm volatile("s_waitcnt vmcnt(0)" ::: "memory");
;         } else {
;             XB_SPIN(xb_ld(&bar[XB_XGEN(b.x)]) == gen, bar);
.LBB0_2142:
	s_or_b64 exec, exec, s[8:9]
	v_cvt_f32_u32_e32 v4, v2
	s_waitcnt vmcnt(0)
	v_readfirstlane_b32 s2, v3
	v_sub_u32_e32 v3, 0, v2
	v_rcp_iflag_f32_e32 v4, v4
	v_add_u32_e32 v5, s2, v1
	v_mul_f32_e32 v4, 0x4f7ffffe, v4
	v_cvt_u32_f32_e32 v4, v4
	v_mul_lo_u32 v1, v3, v4
	v_mul_hi_u32 v1, v4, v1
	v_add_u32_e32 v1, v4, v1
	v_mul_hi_u32 v1, v5, v1
	v_mul_lo_u32 v3, v1, v2
	v_sub_u32_e32 v3, v5, v3
	v_add_u32_e32 v4, 1, v1
	v_cmp_ge_u32_e32 vcc, v3, v2
	s_nop 1
	v_cndmask_b32_e32 v1, v1, v4, vcc
	v_sub_u32_e32 v4, v3, v2
	v_cndmask_b32_e32 v3, v3, v4, vcc
	v_add_u32_e32 v4, 1, v1
	v_cmp_ge_u32_e32 vcc, v3, v2
	v_add_u32_e32 v3, 1, v5
	s_nop 0
	v_cndmask_b32_e32 v1, v1, v4, vcc
	v_mul_lo_u32 v4, v2, v1
	v_add_u32_e32 v2, v4, v2
	v_cmp_ne_u32_e32 vcc, v3, v2
	s_and_saveexec_b64 s[2:3], vcc
	s_xor_b64 s[8:9], exec, s[2:3]
	s_cbranch_execz .LBB0_2156
	s_waitcnt lgkmcnt(0)
	v_mov_b32_e32 v0, 0
	global_load_dword v2, v0, s[68:69] sc1
	s_waitcnt vmcnt(0)
	v_cmp_eq_u32_e32 vcc, v2, v1
	s_and_saveexec_b64 s[10:11], vcc
	s_cbranch_execz .LBB0_2155
	s_mov_b32 s2, 1
	s_mov_b64 s[12:13], 0
	s_branch .LBB0_2146

; __device__ __forceinline__ unsigned xb_ld(unsigned* p)              { return __hip_atomic_load(p, __ATOMIC_RELAXED, __HIP_MEMORY_SCOPE_AGENT); }
; #define XB_SPIN(cond, bar) do { unsigned _sp = 0; while (cond) { __builtin_amdgcn_s_sleep(1); \
;     if ((++_sp & 255u) == 0u) { if (xb_ld(&(bar)[XB_TMO])) break; if (_sp > XB_SPIN_CAP) { atomicAdd(&(bar)[XB_TMO], 1u); break; } } } } while (0)
; __device__ __forceinline__ void xcd_barrier(const XcdBarrier& b) {
;     ...
;             XB_SPIN(xb_ld(&bar[XB_XGEN(b.x)]) == gen, bar);
.LBB0_2150:
	global_load_dword v2, v0, s[68:69] sc1
	s_add_i32 s2, s2, 1
	s_mov_b64 s[18:19], -1
	s_waitcnt vmcnt(0)
	v_cmp_ne_u32_e32 vcc, v2, v1
	s_orn2_b64 s[16:17], vcc, exec
	s_branch .LBB0_2145

; __device__ __forceinline__ unsigned xb_add(unsigned* p, unsigned v) { return __hip_atomic_fetch_add(p, v, __ATOMIC_RELAXED, __HIP_MEMORY_SCOPE_AGENT); }
; __device__ __forceinline__ void xcd_barrier(const XcdBarrier& b) {
;     ...
;             __builtin_amdgcn_fence(__ATOMIC_ACQUIRE, "agent");
;             xb_add(&bar[XB_XGEN(b.x)], 1u);
;             asm volatile("s_waitcnt vmcnt(0)" ::: "memory");
.LBB0_2173:
	s_or_b64 exec, exec, s[8:9]
	s_mov_b64 s[8:9], exec
	v_mbcnt_lo_u32_b32 v0, s8, 0
	v_mbcnt_hi_u32_b32 v0, s9, v0
	v_cmp_eq_u32_e32 vcc, 0, v0
	s_waitcnt vmcnt(0)
	buffer_inv sc1
	s_and_saveexec_b64 s[10:11], vcc
	s_cbranch_execz .LBB0_2175
	s_bcnt1_i32_b64 s2, s[8:9]
	v_mov_b32_e32 v0, 0
	v_mov_b32_e32 v1, s2
.LBB0_2175:
	s_or_b64 exec, exec, s[10:11]
	s_waitcnt vmcnt(0)

; __device__ __forceinline__ unsigned xb_add(unsigned* p, unsigned v) { return __hip_atomic_fetch_add(p, v, __ATOMIC_RELAXED, __HIP_MEMORY_SCOPE_AGENT); }
; __device__ __forceinline__ void xcd_barrier(const XcdBarrier& b) {
;     ...
;             __builtin_amdgcn_fence(__ATOMIC_ACQUIRE, "agent");
;             xb_add(&bar[XB_XGEN(b.x)], 1u);
;             asm volatile("s_waitcnt vmcnt(0)" ::: "memory");
.LBB0_2267:
	s_or_b64 exec, exec, s[8:9]
	s_mov_b64 s[8:9], exec
	v_mbcnt_lo_u32_b32 v0, s8, 0
	v_mbcnt_hi_u32_b32 v0, s9, v0
	v_cmp_eq_u32_e32 vcc, 0, v0
	s_waitcnt vmcnt(0)
	buffer_inv sc1
	s_and_saveexec_b64 s[10:11], vcc
	s_cbranch_execz .LBB0_2269
	s_bcnt1_i32_b64 s2, s[8:9]
	v_mov_b32_e32 v0, 0
	v_mov_b32_e32 v1, s2
.LBB0_2269:
	s_or_b64 exec, exec, s[10:11]
	s_waitcnt vmcnt(0)

; __device__ __forceinline__ unsigned xb_ld(unsigned* p)              { return __hip_atomic_load(p, __ATOMIC_RELAXED, __HIP_MEMORY_SCOPE_AGENT); }
; __device__ __forceinline__ unsigned xb_add(unsigned* p, unsigned v) { return __hip_atomic_fetch_add(p, v, __ATOMIC_RELAXED, __HIP_MEMORY_SCOPE_AGENT); }
; #define XB_SPIN(cond, bar) do { unsigned _sp = 0; while (cond) { __builtin_amdgcn_s_sleep(1); \
;     if ((++_sp & 255u) == 0u) { if (xb_ld(&(bar)[XB_TMO])) break; if (_sp > XB_SPIN_CAP) { atomicAdd(&(bar)[XB_TMO], 1u); break; } } } } while (0)
; __device__ __forceinline__ void xcd_barrier(const XcdBarrier& b) {
;     ...
;         const unsigned old = xb_add(&bar[XB_XSUB(b.x)], 1u);
;         const unsigned gen = old / nloc;
;         if (old + 1u == (gen + 1u) * nloc) {
;             __builtin_amdgcn_fence(__ATOMIC_RELEASE, "agent");
;             asm volatile("s_waitcnt vmcnt(0)" ::: "memory");
;             const unsigned og = xb_add(&bar[XB_TOP], 1u);
;             const unsigned tg = og / nx;
;             if (og + 1u == (tg + 1u) * nx) xb_add(&bar[XB_TOPGEN], 1u);
;             else XB_SPIN(xb_ld(&bar[XB_TOPGEN]) == tg, bar);
;             __builtin_amdgcn_fence(__ATOMIC_ACQUIRE, "agent");
;             xb_add(&bar[XB_XGEN(b.x)], 1u);
;             asm volatile("s_waitcnt vmcnt(0)" ::: "memory");
;         } else {
;             XB_SPIN(xb_ld(&bar[XB_XGEN(b.x)]) == gen, bar);
.LBB0_2370:
	s_or_b64 exec, exec, s[4:5]
	v_cvt_f32_u32_e32 v4, v2
	s_waitcnt vmcnt(0)
	v_readfirstlane_b32 s2, v3
	v_sub_u32_e32 v3, 0, v2
	v_rcp_iflag_f32_e32 v4, v4
	v_add_u32_e32 v5, s2, v1
	v_mul_f32_e32 v4, 0x4f7ffffe, v4
	v_cvt_u32_f32_e32 v4, v4
	v_mul_lo_u32 v1, v3, v4
	v_mul_hi_u32 v1, v4, v1
	v_add_u32_e32 v1, v4, v1
	v_mul_hi_u32 v1, v5, v1
	v_mul_lo_u32 v3, v1, v2
	v_sub_u32_e32 v3, v5, v3
	v_add_u32_e32 v4, 1, v1
	v_cmp_ge_u32_e32 vcc, v3, v2
	s_nop 1
	v_cndmask_b32_e32 v1, v1, v4, vcc
	v_sub_u32_e32 v4, v3, v2
	v_cndmask_b32_e32 v3, v3, v4, vcc
	v_add_u32_e32 v4, 1, v1
	v_cmp_ge_u32_e32 vcc, v3, v2
	v_add_u32_e32 v3, 1, v5
	s_nop 0
	v_cndmask_b32_e32 v1, v1, v4, vcc
	v_mul_lo_u32 v4, v2, v1
	v_add_u32_e32 v2, v4, v2
	v_cmp_ne_u32_e32 vcc, v3, v2
	s_and_saveexec_b64 s[2:3], vcc
	s_xor_b64 s[4:5], exec, s[2:3]
	s_cbranch_execz .LBB0_2384
	s_waitcnt lgkmcnt(0)
	v_mov_b32_e32 v0, 0
	global_load_dword v2, v0, s[68:69] sc1
	s_waitcnt vmcnt(0)
	v_cmp_eq_u32_e32 vcc, v2, v1
	s_and_saveexec_b64 s[8:9], vcc
	s_cbranch_execz .LBB0_2383
	s_mov_b32 s2, 1
	s_mov_b64 s[10:11], 0
	s_branch .LBB0_2374

; __device__ __forceinline__ unsigned xb_ld(unsigned* p)              { return __hip_atomic_load(p, __ATOMIC_RELAXED, __HIP_MEMORY_SCOPE_AGENT); }
; #define XB_SPIN(cond, bar) do { unsigned _sp = 0; while (cond) { __builtin_amdgcn_s_sleep(1); \
;     if ((++_sp & 255u) == 0u) { if (xb_ld(&(bar)[XB_TMO])) break; if (_sp > XB_SPIN_CAP) { atomicAdd(&(bar)[XB_TMO], 1u); break; } } } } while (0)
; __device__ __forceinline__ void xcd_barrier(const XcdBarrier& b) {
;     ...
;             XB_SPIN(xb_ld(&bar[XB_XGEN(b.x)]) == gen, bar);
.LBB0_2378:
	global_load_dword v2, v0, s[68:69] sc1
	s_add_i32 s2, s2, 1
	s_mov_b64 s[16:17], -1
	s_waitcnt vmcnt(0)
	v_cmp_ne_u32_e32 vcc, v2, v1
	s_orn2_b64 s[14:15], vcc, exec
	s_branch .LBB0_2373

; __device__ __forceinline__ unsigned xb_add(unsigned* p, unsigned v) { return __hip_atomic_fetch_add(p, v, __ATOMIC_RELAXED, __HIP_MEMORY_SCOPE_AGENT); }
; __device__ __forceinline__ void xcd_barrier(const XcdBarrier& b) {
;     ...
;             __builtin_amdgcn_fence(__ATOMIC_ACQUIRE, "agent");
;             xb_add(&bar[XB_XGEN(b.x)], 1u);
;             asm volatile("s_waitcnt vmcnt(0)" ::: "memory");
.LBB0_2401:
	s_or_b64 exec, exec, s[4:5]
	s_mov_b64 s[4:5], exec
	v_mbcnt_lo_u32_b32 v0, s4, 0
	v_mbcnt_hi_u32_b32 v0, s5, v0
	v_cmp_eq_u32_e32 vcc, 0, v0
	s_waitcnt vmcnt(0)
	buffer_inv sc1
	s_and_saveexec_b64 s[8:9], vcc
	s_cbranch_execz .LBB0_2403
	s_bcnt1_i32_b64 s2, s[4:5]
	v_mov_b32_e32 v0, 0
	v_mov_b32_e32 v1, s2
.LBB0_2403:
	s_or_b64 exec, exec, s[8:9]
	s_waitcnt vmcnt(0)

; __device__ __forceinline__ unsigned xb_add(unsigned* p, unsigned v) { return __hip_atomic_fetch_add(p, v, __ATOMIC_RELAXED, __HIP_MEMORY_SCOPE_AGENT); }
; __device__ __forceinline__ void xcd_barrier(const XcdBarrier& b) {
;     ...
;             __builtin_amdgcn_fence(__ATOMIC_ACQUIRE, "agent");
;             xb_add(&bar[XB_XGEN(b.x)], 1u);
;             asm volatile("s_waitcnt vmcnt(0)" ::: "memory");
.LBB0_2499:
	s_or_b64 exec, exec, s[4:5]
	s_mov_b64 s[4:5], exec
	v_mbcnt_lo_u32_b32 v0, s4, 0
	v_mbcnt_hi_u32_b32 v0, s5, v0
	v_cmp_eq_u32_e32 vcc, 0, v0
	s_waitcnt vmcnt(0)
	buffer_inv sc1
	s_and_saveexec_b64 s[8:9], vcc
	s_cbranch_execz .LBB0_2501
	s_bcnt1_i32_b64 s2, s[4:5]
	v_mov_b32_e32 v0, 0
	v_mov_b32_e32 v1, s2
.LBB0_2501:
	s_or_b64 exec, exec, s[8:9]
	s_waitcnt vmcnt(0)

; __device__ __forceinline__ unsigned xb_add(unsigned* p, unsigned v) { return __hip_atomic_fetch_add(p, v, __ATOMIC_RELAXED, __HIP_MEMORY_SCOPE_AGENT); }
; __device__ __forceinline__ void xcd_barrier(const XcdBarrier& b) {
;     ...
;             __builtin_amdgcn_fence(__ATOMIC_ACQUIRE, "agent");
;             xb_add(&bar[XB_XGEN(b.x)], 1u);
;             asm volatile("s_waitcnt vmcnt(0)" ::: "memory");
.LBB0_2679:
	s_or_b64 exec, exec, s[4:5]
	s_mov_b64 s[4:5], exec
	v_mbcnt_lo_u32_b32 v0, s4, 0
	v_mbcnt_hi_u32_b32 v0, s5, v0
	v_cmp_eq_u32_e32 vcc, 0, v0
	s_waitcnt vmcnt(0)
	buffer_inv sc1
	s_and_saveexec_b64 s[8:9], vcc
	s_cbranch_execz .LBB0_2681
	s_bcnt1_i32_b64 s2, s[4:5]
	v_mov_b32_e32 v0, 0
	v_mov_b32_e32 v1, s2
.LBB0_2681:
	s_or_b64 exec, exec, s[8:9]
	s_waitcnt vmcnt(0)

; __device__ __forceinline__ unsigned xb_add(unsigned* p, unsigned v) { return __hip_atomic_fetch_add(p, v, __ATOMIC_RELAXED, __HIP_MEMORY_SCOPE_AGENT); }
; __device__ __forceinline__ void xcd_barrier(const XcdBarrier& b) {
;     ...
;             __builtin_amdgcn_fence(__ATOMIC_ACQUIRE, "agent");
;             xb_add(&bar[XB_XGEN(b.x)], 1u);
;             asm volatile("s_waitcnt vmcnt(0)" ::: "memory");
.LBB0_2738:
	s_or_b64 exec, exec, s[4:5]
	s_mov_b64 s[4:5], exec
	v_mbcnt_lo_u32_b32 v0, s4, 0
	v_mbcnt_hi_u32_b32 v0, s5, v0
	v_cmp_eq_u32_e32 vcc, 0, v0
	s_waitcnt vmcnt(0)
	buffer_inv sc1
	s_and_saveexec_b64 s[8:9], vcc
	s_cbranch_execz .LBB0_2740
	s_bcnt1_i32_b64 s2, s[4:5]
	v_mov_b32_e32 v0, 0
	v_mov_b32_e32 v1, s2
.LBB0_2740:
	s_or_b64 exec, exec, s[8:9]
	s_waitcnt vmcnt(0)

; __device__ __forceinline__ unsigned xb_ld(unsigned* p)              { return __hip_atomic_load(p, __ATOMIC_RELAXED, __HIP_MEMORY_SCOPE_AGENT); }
; __device__ __forceinline__ unsigned xb_add(unsigned* p, unsigned v) { return __hip_atomic_fetch_add(p, v, __ATOMIC_RELAXED, __HIP_MEMORY_SCOPE_AGENT); }
; #define XB_SPIN(cond, bar) do { unsigned _sp = 0; while (cond) { __builtin_amdgcn_s_sleep(1); \
;     if ((++_sp & 255u) == 0u) { if (xb_ld(&(bar)[XB_TMO])) break; if (_sp > XB_SPIN_CAP) { atomicAdd(&(bar)[XB_TMO], 1u); break; } } } } while (0)
; __device__ __forceinline__ void xcd_barrier(const XcdBarrier& b) {
;     ...
;         const unsigned old = xb_add(&bar[XB_XSUB(b.x)], 1u);
;         const unsigned gen = old / nloc;
;         if (old + 1u == (gen + 1u) * nloc) {
;             __builtin_amdgcn_fence(__ATOMIC_RELEASE, "agent");
;             asm volatile("s_waitcnt vmcnt(0)" ::: "memory");
;             const unsigned og = xb_add(&bar[XB_TOP], 1u);
;             const unsigned tg = og / nx;
;             if (og + 1u == (tg + 1u) * nx) xb_add(&bar[XB_TOPGEN], 1u);
;             else XB_SPIN(xb_ld(&bar[XB_TOPGEN]) == tg, bar);
;             __builtin_amdgcn_fence(__ATOMIC_ACQUIRE, "agent");
;             xb_add(&bar[XB_XGEN(b.x)], 1u);
;             asm volatile("s_waitcnt vmcnt(0)" ::: "memory");
;         } else {
;             XB_SPIN(xb_ld(&bar[XB_XGEN(b.x)]) == gen, bar);
.LBB0_2793:
	s_or_b64 exec, exec, s[4:5]
	v_cvt_f32_u32_e32 v4, v2
	s_waitcnt vmcnt(0)
	v_readfirstlane_b32 s2, v3
	v_sub_u32_e32 v3, 0, v2
	v_rcp_iflag_f32_e32 v4, v4
	v_add_u32_e32 v5, s2, v1
	v_mul_f32_e32 v4, 0x4f7ffffe, v4
	v_cvt_u32_f32_e32 v4, v4
	v_mul_lo_u32 v1, v3, v4
	v_mul_hi_u32 v1, v4, v1
	v_add_u32_e32 v1, v4, v1
	v_mul_hi_u32 v1, v5, v1
	v_mul_lo_u32 v3, v1, v2
	v_sub_u32_e32 v3, v5, v3
	v_add_u32_e32 v4, 1, v1
	v_cmp_ge_u32_e32 vcc, v3, v2
	s_nop 1
	v_cndmask_b32_e32 v1, v1, v4, vcc
	v_sub_u32_e32 v4, v3, v2
	v_cndmask_b32_e32 v3, v3, v4, vcc
	v_add_u32_e32 v4, 1, v1
	v_cmp_ge_u32_e32 vcc, v3, v2
	v_add_u32_e32 v3, 1, v5
	s_nop 0
	v_cndmask_b32_e32 v1, v1, v4, vcc
	v_mul_lo_u32 v4, v2, v1
	v_add_u32_e32 v2, v4, v2
	v_cmp_ne_u32_e32 vcc, v3, v2
	s_and_saveexec_b64 s[2:3], vcc
	s_xor_b64 s[4:5], exec, s[2:3]
	s_cbranch_execz .LBB0_2807
	s_waitcnt lgkmcnt(0)
	v_mov_b32_e32 v0, 0
	global_load_dword v2, v0, s[68:69] sc1
	s_waitcnt vmcnt(0)
	v_cmp_eq_u32_e32 vcc, v2, v1
	s_and_saveexec_b64 s[6:7], vcc
	s_cbranch_execz .LBB0_2806
	s_mov_b32 s2, 1
	s_mov_b64 s[8:9], 0
	s_branch .LBB0_2797

; __device__ __forceinline__ unsigned xb_ld(unsigned* p)              { return __hip_atomic_load(p, __ATOMIC_RELAXED, __HIP_MEMORY_SCOPE_AGENT); }
; #define XB_SPIN(cond, bar) do { unsigned _sp = 0; while (cond) { __builtin_amdgcn_s_sleep(1); \
;     if ((++_sp & 255u) == 0u) { if (xb_ld(&(bar)[XB_TMO])) break; if (_sp > XB_SPIN_CAP) { atomicAdd(&(bar)[XB_TMO], 1u); break; } } } } while (0)
; __device__ __forceinline__ void xcd_barrier(const XcdBarrier& b) {
;     ...
;             XB_SPIN(xb_ld(&bar[XB_XGEN(b.x)]) == gen, bar);
.LBB0_2801:
	global_load_dword v2, v0, s[68:69] sc1
	s_add_i32 s2, s2, 1
	s_mov_b64 s[14:15], -1
	s_waitcnt vmcnt(0)
	v_cmp_ne_u32_e32 vcc, v2, v1
	s_orn2_b64 s[12:13], vcc, exec
	s_branch .LBB0_2796

; __device__ __forceinline__ unsigned xb_add(unsigned* p, unsigned v) { return __hip_atomic_fetch_add(p, v, __ATOMIC_RELAXED, __HIP_MEMORY_SCOPE_AGENT); }
; __device__ __forceinline__ void xcd_barrier(const XcdBarrier& b) {
;     ...
;             __builtin_amdgcn_fence(__ATOMIC_ACQUIRE, "agent");
;             xb_add(&bar[XB_XGEN(b.x)], 1u);
;             asm volatile("s_waitcnt vmcnt(0)" ::: "memory");
.LBB0_2824:
	s_or_b64 exec, exec, s[4:5]
	s_mov_b64 s[4:5], exec
	v_mbcnt_lo_u32_b32 v0, s4, 0
	v_mbcnt_hi_u32_b32 v0, s5, v0
	v_cmp_eq_u32_e32 vcc, 0, v0
	s_waitcnt vmcnt(0)
	buffer_inv sc1
	s_and_saveexec_b64 s[6:7], vcc
	s_cbranch_execz .LBB0_2826
	s_bcnt1_i32_b64 s2, s[4:5]
	v_mov_b32_e32 v0, 0
	v_mov_b32_e32 v1, s2
.LBB0_2826:
	s_or_b64 exec, exec, s[6:7]
	s_waitcnt vmcnt(0)

; __device__ __forceinline__ unsigned xb_add(unsigned* p, unsigned v) { return __hip_atomic_fetch_add(p, v, __ATOMIC_RELAXED, __HIP_MEMORY_SCOPE_AGENT); }
; __device__ __forceinline__ void xcd_barrier(const XcdBarrier& b) {
;     ...
;             __builtin_amdgcn_fence(__ATOMIC_ACQUIRE, "agent");
;             xb_add(&bar[XB_XGEN(b.x)], 1u);
;             asm volatile("s_waitcnt vmcnt(0)" ::: "memory");
.LBB0_2918:
	s_or_b64 exec, exec, s[4:5]
	s_mov_b64 s[4:5], exec
	v_mbcnt_lo_u32_b32 v0, s4, 0
	v_mbcnt_hi_u32_b32 v0, s5, v0
	v_cmp_eq_u32_e32 vcc, 0, v0
	s_waitcnt vmcnt(0)
	buffer_inv sc1
	s_and_saveexec_b64 s[6:7], vcc
	s_cbranch_execz .LBB0_2920
	s_bcnt1_i32_b64 s2, s[4:5]
	v_mov_b32_e32 v0, 0
	v_mov_b32_e32 v1, s2
.LBB0_2920:
	s_or_b64 exec, exec, s[6:7]
	s_waitcnt vmcnt(0)

; __device__ __forceinline__ unsigned xb_add(unsigned* p, unsigned v) { return __hip_atomic_fetch_add(p, v, __ATOMIC_RELAXED, __HIP_MEMORY_SCOPE_AGENT); }
; __device__ __forceinline__ void xcd_barrier(const XcdBarrier& b) {
;     ...
;             __builtin_amdgcn_fence(__ATOMIC_ACQUIRE, "agent");
;             xb_add(&bar[XB_XGEN(b.x)], 1u);
;             asm volatile("s_waitcnt vmcnt(0)" ::: "memory");
.LBB0_3014:
	s_or_b64 exec, exec, s[4:5]
	s_mov_b64 s[4:5], exec
	v_mbcnt_lo_u32_b32 v0, s4, 0
	v_mbcnt_hi_u32_b32 v0, s5, v0
	v_cmp_eq_u32_e32 vcc, 0, v0
	s_waitcnt vmcnt(0)
	buffer_inv sc1
	s_and_saveexec_b64 s[6:7], vcc
	s_cbranch_execz .LBB0_3016
	s_bcnt1_i32_b64 s2, s[4:5]
	v_mov_b32_e32 v0, 0
	v_mov_b32_e32 v1, s2
.LBB0_3016:
	s_or_b64 exec, exec, s[6:7]
	s_waitcnt vmcnt(0)

; __device__ __forceinline__ unsigned xb_ld(unsigned* p)              { return __hip_atomic_load(p, __ATOMIC_RELAXED, __HIP_MEMORY_SCOPE_AGENT); }
; __device__ __forceinline__ unsigned xb_add(unsigned* p, unsigned v) { return __hip_atomic_fetch_add(p, v, __ATOMIC_RELAXED, __HIP_MEMORY_SCOPE_AGENT); }
; #define XB_SPIN(cond, bar) do { unsigned _sp = 0; while (cond) { __builtin_amdgcn_s_sleep(1); \
;     if ((++_sp & 255u) == 0u) { if (xb_ld(&(bar)[XB_TMO])) break; if (_sp > XB_SPIN_CAP) { atomicAdd(&(bar)[XB_TMO], 1u); break; } } } } while (0)
; __device__ __forceinline__ void xcd_barrier(const XcdBarrier& b) {
;     ...
;         const unsigned old = xb_add(&bar[XB_XSUB(b.x)], 1u);
;         const unsigned gen = old / nloc;
;         if (old + 1u == (gen + 1u) * nloc) {
;             __builtin_amdgcn_fence(__ATOMIC_RELEASE, "agent");
;             asm volatile("s_waitcnt vmcnt(0)" ::: "memory");
;             const unsigned og = xb_add(&bar[XB_TOP], 1u);
;             const unsigned tg = og / nx;
;             if (og + 1u == (tg + 1u) * nx) xb_add(&bar[XB_TOPGEN], 1u);
;             else XB_SPIN(xb_ld(&bar[XB_TOPGEN]) == tg, bar);
;             __builtin_amdgcn_fence(__ATOMIC_ACQUIRE, "agent");
;             xb_add(&bar[XB_XGEN(b.x)], 1u);
;             asm volatile("s_waitcnt vmcnt(0)" ::: "memory");
;         } else {
;             XB_SPIN(xb_ld(&bar[XB_XGEN(b.x)]) == gen, bar);
.LBB0_3081:
	s_or_b64 exec, exec, s[2:3]
	v_cvt_f32_u32_e32 v4, v2
	s_waitcnt vmcnt(0)
	v_readfirstlane_b32 s2, v3
	v_sub_u32_e32 v3, 0, v2
	v_rcp_iflag_f32_e32 v4, v4
	v_add_u32_e32 v5, s2, v1
	v_mul_f32_e32 v4, 0x4f7ffffe, v4
	v_cvt_u32_f32_e32 v4, v4
	v_mul_lo_u32 v1, v3, v4
	v_mul_hi_u32 v1, v4, v1
	v_add_u32_e32 v1, v4, v1
	v_mul_hi_u32 v1, v5, v1
	v_mul_lo_u32 v3, v1, v2
	v_sub_u32_e32 v3, v5, v3
	v_add_u32_e32 v4, 1, v1
	v_cmp_ge_u32_e32 vcc, v3, v2
	s_nop 1
	v_cndmask_b32_e32 v1, v1, v4, vcc
	v_sub_u32_e32 v4, v3, v2
	v_cndmask_b32_e32 v3, v3, v4, vcc
	v_add_u32_e32 v4, 1, v1
	v_cmp_ge_u32_e32 vcc, v3, v2
	v_add_u32_e32 v3, 1, v5
	s_nop 0
	v_cndmask_b32_e32 v1, v1, v4, vcc
	v_mul_lo_u32 v4, v2, v1
	v_add_u32_e32 v2, v4, v2
	v_cmp_ne_u32_e32 vcc, v3, v2
	s_and_saveexec_b64 s[2:3], vcc
	s_xor_b64 s[2:3], exec, s[2:3]
	s_cbranch_execz .LBB0_3095
	s_waitcnt lgkmcnt(0)
	v_mov_b32_e32 v0, 0
	global_load_dword v2, v0, s[68:69] sc1
	s_waitcnt vmcnt(0)
	v_cmp_eq_u32_e32 vcc, v2, v1
	s_and_saveexec_b64 s[4:5], vcc
	s_cbranch_execz .LBB0_3094
	s_mov_b32 s16, 1
	s_mov_b64 s[6:7], 0
	s_branch .LBB0_3085

; __device__ __forceinline__ unsigned xb_ld(unsigned* p)              { return __hip_atomic_load(p, __ATOMIC_RELAXED, __HIP_MEMORY_SCOPE_AGENT); }
; #define XB_SPIN(cond, bar) do { unsigned _sp = 0; while (cond) { __builtin_amdgcn_s_sleep(1); \
;     if ((++_sp & 255u) == 0u) { if (xb_ld(&(bar)[XB_TMO])) break; if (_sp > XB_SPIN_CAP) { atomicAdd(&(bar)[XB_TMO], 1u); break; } } } } while (0)
; __device__ __forceinline__ void xcd_barrier(const XcdBarrier& b) {
;     ...
;             XB_SPIN(xb_ld(&bar[XB_XGEN(b.x)]) == gen, bar);
.LBB0_3089:
	global_load_dword v2, v0, s[68:69] sc1
	s_add_i32 s16, s16, 1
	s_mov_b64 s[12:13], -1
	s_waitcnt vmcnt(0)
	v_cmp_ne_u32_e32 vcc, v2, v1
	s_orn2_b64 s[10:11], vcc, exec
	s_branch .LBB0_3084

; __device__ __forceinline__ unsigned xb_add(unsigned* p, unsigned v) { return __hip_atomic_fetch_add(p, v, __ATOMIC_RELAXED, __HIP_MEMORY_SCOPE_AGENT); }
; __device__ __forceinline__ void xcd_barrier(const XcdBarrier& b) {
;     ...
;             __builtin_amdgcn_fence(__ATOMIC_ACQUIRE, "agent");
;             xb_add(&bar[XB_XGEN(b.x)], 1u);
;             asm volatile("s_waitcnt vmcnt(0)" ::: "memory");
.LBB0_3112:
	s_or_b64 exec, exec, s[2:3]
	s_mov_b64 s[2:3], exec
	v_mbcnt_lo_u32_b32 v0, s2, 0
	v_mbcnt_hi_u32_b32 v0, s3, v0
	v_cmp_eq_u32_e32 vcc, 0, v0
	s_waitcnt vmcnt(0)
	buffer_inv sc1
	s_and_saveexec_b64 s[4:5], vcc
	s_cbranch_execz .LBB0_3114
	s_bcnt1_i32_b64 s2, s[2:3]
	v_mov_b32_e32 v0, 0
	v_mov_b32_e32 v1, s2
.LBB0_3114:
	s_or_b64 exec, exec, s[4:5]
	s_waitcnt vmcnt(0)
